# MLA: rendezvous after the 17th S1 MFMA with the K,pe,V staging write order (staging behind the 19th MFMA)
# baseline (speedup 1.0000x reference)
; __device__ __forceinline__ void mla_qkt_neg(f32x16& p0, f32x16& p1, const f32x16& negm, const unsigned char* Kb, const bf16x8* qr, int r32, int hi) {
; #pragma unroll
;     for (int d0 = 0; d0 < 6; ++d0) { const int cb = (d0 * 16 + hi * 8) * 2;
;         const bf16x8 b0 = *(const bf16x8*)(Kb + r32 * KSTR + cb), b1 = *(const bf16x8*)(Kb + (32 + r32) * KSTR + cb);
;         if (d0 == 0) { p0 = __builtin_amdgcn_mfma_f32_32x32x16_bf16(b0, qr[0], negm, 0, 0, 0); p1 = __builtin_amdgcn_mfma_f32_32x32x16_bf16(b1, qr[0], negm, 0, 0, 0); }
;         else { p0 = __builtin_amdgcn_mfma_f32_32x32x16_bf16(b0, qr[d0], p0, 0, 0, 0); p1 = __builtin_amdgcn_mfma_f32_32x32x16_bf16(b1, qr[d0], p1, 0, 0, 0); } }
; }
; __device__ __forceinline__ void pv_both_kp(f32x16& o0, f32x16& o1, int vb, bf16x8 pa0, bf16x8 pa1, bf16x8 pa2, bf16x8 pa3) {
;     const s16x4 l0 = tr_read<v_rd_off_kp(0, 0, 0)>(vb), h0 = tr_read<v_rd_off_kp(0, 0, 1)>(vb), l1 = tr_read<v_rd_off_kp(0, 1, 0)>(vb), h1 = tr_read<v_rd_off_kp(0, 1, 1)>(vb);
;     const s16x4 l2 = tr_read<v_rd_off_kp(0, 2, 0)>(vb), h2 = tr_read<v_rd_off_kp(0, 2, 1)>(vb), l3 = tr_read<v_rd_off_kp(0, 3, 0)>(vb), h3 = tr_read<v_rd_off_kp(0, 3, 1)>(vb);
;     const s16x4 m0 = tr_read<v_rd_off_kp(1, 0, 0)>(vb), n0 = tr_read<v_rd_off_kp(1, 0, 1)>(vb), m1 = tr_read<v_rd_off_kp(1, 1, 0)>(vb), n1 = tr_read<v_rd_off_kp(1, 1, 1)>(vb);
;     const s16x4 m2 = tr_read<v_rd_off_kp(1, 2, 0)>(vb), n2 = tr_read<v_rd_off_kp(1, 2, 1)>(vb), m3 = tr_read<v_rd_off_kp(1, 3, 0)>(vb), n3 = tr_read<v_rd_off_kp(1, 3, 1)>(vb);
;     asm volatile("s_waitcnt lgkmcnt(8)" ::: "memory"); __builtin_amdgcn_sched_barrier(0);
;     ...
;     o0 = __builtin_amdgcn_mfma_f32_32x32x16_bf16(pa0, PK(l0, h0), o0, 0, 0, 0);
;     o0 = __builtin_amdgcn_mfma_f32_32x32x16_bf16(pa1, PK(l1, h1), o0, 0, 0, 0);
;     o0 = __builtin_amdgcn_mfma_f32_32x32x16_bf16(pa2, PK(l2, h2), o0, 0, 0, 0);
;     o0 = __builtin_amdgcn_mfma_f32_32x32x16_bf16(pa3, PK(l3, h3), o0, 0, 0, 0);
;     asm volatile("s_waitcnt lgkmcnt(0)" ::: "memory"); __builtin_amdgcn_sched_barrier(0);
;     o1 = __builtin_amdgcn_mfma_f32_32x32x16_bf16(pa0, PK(m0, n0), o1, 0, 0, 0);
;     o1 = __builtin_amdgcn_mfma_f32_32x32x16_bf16(pa1, PK(m1, n1), o1, 0, 0, 0);
;     o1 = __builtin_amdgcn_mfma_f32_32x32x16_bf16(pa2, PK(m2, n2), o1, 0, 0, 0);
;     o1 = __builtin_amdgcn_mfma_f32_32x32x16_bf16(pa3, PK(m3, n3), o1, 0, 0, 0);
;     ...
; }
.LBB0_969:
	s_waitcnt lgkmcnt(3)
	v_mfma_f32_32x32x16_bf16 v[64:79], v[80:83], v[96:99], v[32:47]
	s_waitcnt lgkmcnt(2)
	v_mfma_f32_32x32x16_bf16 v[80:95], v[150:153], v[96:99], v[32:47]
	s_waitcnt lgkmcnt(1)
	v_mfma_f32_32x32x16_bf16 v[64:79], v[146:149], v[100:103], v[64:79]
	ds_read_b128 v[162:165], v157 offset:64
	ds_read_b128 v[150:153], v157 offset:6720
	s_waitcnt lgkmcnt(2)
	v_mfma_f32_32x32x16_bf16 v[80:95], v[168:171], v[100:103], v[80:95]
	s_waitcnt lgkmcnt(1)
	v_mfma_f32_32x32x16_bf16 v[64:79], v[162:165], v[104:107], v[64:79]
	ds_read_b128 v[146:149], v157 offset:96
	ds_read_b128 v[168:171], v157 offset:6752
	s_waitcnt lgkmcnt(2)
	v_mfma_f32_32x32x16_bf16 v[80:95], v[150:153], v[104:107], v[80:95]
	s_waitcnt lgkmcnt(1)
	v_mfma_f32_32x32x16_bf16 v[64:79], v[146:149], v[108:111], v[64:79]
	ds_read_b128 v[162:165], v157 offset:128
	ds_read_b128 v[150:153], v157 offset:6784
	s_waitcnt lgkmcnt(2)
	v_mfma_f32_32x32x16_bf16 v[80:95], v[168:171], v[108:111], v[80:95]
	s_waitcnt lgkmcnt(1)
	v_mfma_f32_32x32x16_bf16 v[64:79], v[162:165], v[112:115], v[64:79]
	ds_read_b128 v[168:171], v157 offset:160
	ds_read_b128 v[162:165], v157 offset:6816
	ds_read_b64_tr_b16 v[182:183], v204 offset:0
	ds_read_b64_tr_b16 v[184:185], v204 offset:0x100
	s_waitcnt lgkmcnt(4)
	v_mfma_f32_32x32x16_bf16 v[80:95], v[150:153], v[112:115], v[80:95]
	ds_read_b64_tr_b16 v[146:147], v204 offset:0x800
	ds_read_b64_tr_b16 v[148:149], v204 offset:0x900
	ds_read_b64_tr_b16 v[186:187], v204 offset:0x1000
	ds_read_b64_tr_b16 v[188:189], v204 offset:0x1100
	ds_read_b64_tr_b16 v[190:191], v204 offset:0x1800
	ds_read_b64_tr_b16 v[192:193], v204 offset:0x1900
	ds_read_b64_tr_b16 v[206:207], v204 offset:0x200
	ds_read_b64_tr_b16 v[208:209], v204 offset:0x300
	s_waitcnt lgkmcnt(11)
	v_mfma_f32_32x32x16_bf16 v[64:79], v[168:171], v[116:119], v[64:79]
	ds_read_b64_tr_b16 v[150:151], v204 offset:0xa00
	ds_read_b64_tr_b16 v[152:153], v204 offset:0xb00
	ds_read_b64_tr_b16 v[210:211], v204 offset:0x1200
	ds_read_b64_tr_b16 v[212:213], v204 offset:0x1300
	ds_read_b64_tr_b16 v[214:215], v204 offset:0x1a00
	ds_read_b64_tr_b16 v[216:217], v204 offset:0x1b00
	s_waitcnt lgkmcnt(0)
	v_mfma_f32_32x32x16_bf16 v[80:95], v[162:165], v[116:119], v[80:95]
	v_mfma_f32_32x32x16_bf16 v[0:15], v[60:63], v[182:185], v[0:15]
	v_mfma_f32_32x32x16_bf16 v[0:15], v[56:59], v[146:149], v[0:15]
	v_mfma_f32_32x32x16_bf16 v[0:15], v[52:55], v[186:189], v[0:15]
	v_mfma_f32_32x32x16_bf16 v[0:15], v[48:51], v[190:193], v[0:15]
	v_mfma_f32_32x32x16_bf16 v[16:31], v[60:63], v[206:209], v[16:31]
	s_waitcnt lgkmcnt(0)
	s_cmp_lg_u32 s40, 0
	s_cbranch_scc0 .Lmla_nobar4
	s_barrier
.Lmla_nobar4:
	v_mfma_f32_32x32x16_bf16 v[16:31], v[56:59], v[150:153], v[16:31]
	v_mfma_f32_32x32x16_bf16 v[16:31], v[52:55], v[210:213], v[16:31]
	s_cmp_lg_u64 s[44:45], 0
	s_cbranch_scc0 .Lmla_w1_tail
	s_waitcnt vmcnt(3)
	ds_write_b128 v196, v[120:123]
	s_cmp_lg_u32 s8, 0
	s_cbranch_scc0 .Lmla_nope_e
	ds_write_b128 v238, v[124:127] offset:128

; __device__ __forceinline__ void mla_softmax_rel_kp(f32x16& p0, f32x16& p1, f32x16& negm, bool first, float& l_reg, float& alpha, bf16x8& pa0, bf16x8& pa1, bf16x8& pa2, bf16x8& pa3) {
;     ...
;         for (int r = 0; r < 16; ++r) { negm[r] = nm; p0[r] -= d; p1[r] -= d; }
;     }
; #pragma unroll
;     for (int r = 0; r < 16; ++r) { p0[r] = __builtin_amdgcn_exp2f(p0[r]); p1[r] = __builtin_amdgcn_exp2f(p1[r]); }
;     float ps = 0.f;
; #pragma unroll
;     for (int r = 0; r < 16; ++r) ps += p0[r];
; #pragma unroll
;     for (int r = 0; r < 16; ++r) ps += p1[r];
;     { auto rr = __builtin_amdgcn_permlane32_swap(__float_as_uint(ps), __float_as_uint(ps), false, false); ps = __uint_as_float(rr[0]) + __uint_as_float(rr[1]); }
;     l_reg = l_reg * alpha + ps;
.LBB0_975:
	v_mfma_f32_32x32x16_bf16 v[16:31], v[48:51], v[214:217], v[16:31]
	v_exp_f32_e32 v218, v64
	v_exp_f32_e32 v219, v65
	v_exp_f32_e32 v220, v66
	v_exp_f32_e32 v221, v67
	v_add_f32_e32 v173, v218, v220
	v_exp_f32_e32 v222, v68
	v_add_f32_e32 v174, v219, v221
	v_exp_f32_e32 v223, v69
	v_add_f32_e32 v173, v222, v173
	v_exp_f32_e32 v224, v70
	v_add_f32_e32 v174, v223, v174
	v_exp_f32_e32 v225, v71
	v_add_f32_e32 v173, v224, v173
	v_exp_f32_e32 v226, v72
	v_add_f32_e32 v174, v225, v174
	v_exp_f32_e32 v227, v73
	v_add_f32_e32 v173, v226, v173
	v_exp_f32_e32 v228, v74
	v_add_f32_e32 v174, v227, v174
	v_exp_f32_e32 v229, v75
	v_add_f32_e32 v173, v228, v173
	v_exp_f32_e32 v230, v76
	v_add_f32_e32 v174, v229, v174
	v_exp_f32_e32 v231, v77
	v_add_f32_e32 v173, v230, v173
	v_exp_f32_e32 v232, v78
	v_add_f32_e32 v174, v231, v174
	v_exp_f32_e32 v233, v79
	v_add_f32_e32 v173, v232, v173
	v_exp_f32_e32 v234, v80
	v_add_f32_e32 v174, v233, v174
	v_exp_f32_e32 v240, v81
	v_add_f32_e32 v173, v234, v173
	v_exp_f32_e32 v241, v82
	v_add_f32_e32 v174, v240, v174
	v_exp_f32_e32 v242, v83
	v_add_f32_e32 v173, v241, v173
	v_exp_f32_e32 v243, v84
	v_add_f32_e32 v174, v242, v174
	v_exp_f32_e32 v244, v85
	v_add_f32_e32 v173, v243, v173
	v_exp_f32_e32 v245, v86
	v_add_f32_e32 v174, v244, v174
	v_exp_f32_e32 v246, v87
	v_add_f32_e32 v173, v245, v173
	v_exp_f32_e32 v247, v88
	v_add_f32_e32 v174, v246, v174
	v_exp_f32_e32 v248, v89
	v_add_f32_e32 v173, v247, v173
	v_exp_f32_e32 v249, v90
	v_add_f32_e32 v174, v248, v174
	v_exp_f32_e32 v250, v91
	v_add_f32_e32 v173, v249, v173
	v_exp_f32_e32 v251, v92
	v_add_f32_e32 v174, v250, v174
	v_exp_f32_e32 v252, v93
	v_add_f32_e32 v173, v251, v173
	v_exp_f32_e32 v253, v94
	v_add_f32_e32 v174, v252, v174
	v_exp_f32_e32 v172, v95
	v_add_f32_e32 v173, v253, v173
	v_add_f32_e32 v174, v172, v174
	v_add_f32_e32 v173, v173, v174
	v_cmp_ge_f32_e32 vcc, 0x47800000, v173
	s_cmp_eq_u64 vcc, exec
	s_cbranch_scc0 .LBB0_995
	v_add_f32_e32 v236, v236, v173

; __device__ __forceinline__ void mla_qkt_neg(f32x16& p0, f32x16& p1, const f32x16& negm, const unsigned char* Kb, const bf16x8* qr, int r32, int hi) {
; #pragma unroll
;     for (int d0 = 0; d0 < 6; ++d0) { const int cb = (d0 * 16 + hi * 8) * 2;
;         const bf16x8 b0 = *(const bf16x8*)(Kb + r32 * KSTR + cb), b1 = *(const bf16x8*)(Kb + (32 + r32) * KSTR + cb);
;         if (d0 == 0) { p0 = __builtin_amdgcn_mfma_f32_32x32x16_bf16(b0, qr[0], negm, 0, 0, 0); p1 = __builtin_amdgcn_mfma_f32_32x32x16_bf16(b1, qr[0], negm, 0, 0, 0); }
;         else { p0 = __builtin_amdgcn_mfma_f32_32x32x16_bf16(b0, qr[d0], p0, 0, 0, 0); p1 = __builtin_amdgcn_mfma_f32_32x32x16_bf16(b1, qr[d0], p1, 0, 0, 0); } }
; }
; __device__ __forceinline__ void pv_both_kp(f32x16& o0, f32x16& o1, int vb, bf16x8 pa0, bf16x8 pa1, bf16x8 pa2, bf16x8 pa3) {
;     const s16x4 l0 = tr_read<v_rd_off_kp(0, 0, 0)>(vb), h0 = tr_read<v_rd_off_kp(0, 0, 1)>(vb), l1 = tr_read<v_rd_off_kp(0, 1, 0)>(vb), h1 = tr_read<v_rd_off_kp(0, 1, 1)>(vb);
;     const s16x4 l2 = tr_read<v_rd_off_kp(0, 2, 0)>(vb), h2 = tr_read<v_rd_off_kp(0, 2, 1)>(vb), l3 = tr_read<v_rd_off_kp(0, 3, 0)>(vb), h3 = tr_read<v_rd_off_kp(0, 3, 1)>(vb);
;     const s16x4 m0 = tr_read<v_rd_off_kp(1, 0, 0)>(vb), n0 = tr_read<v_rd_off_kp(1, 0, 1)>(vb), m1 = tr_read<v_rd_off_kp(1, 1, 0)>(vb), n1 = tr_read<v_rd_off_kp(1, 1, 1)>(vb);
;     const s16x4 m2 = tr_read<v_rd_off_kp(1, 2, 0)>(vb), n2 = tr_read<v_rd_off_kp(1, 2, 1)>(vb), m3 = tr_read<v_rd_off_kp(1, 3, 0)>(vb), n3 = tr_read<v_rd_off_kp(1, 3, 1)>(vb);
;     asm volatile("s_waitcnt lgkmcnt(8)" ::: "memory"); __builtin_amdgcn_sched_barrier(0);
;     ...
;     o0 = __builtin_amdgcn_mfma_f32_32x32x16_bf16(pa0, PK(l0, h0), o0, 0, 0, 0);
;     o0 = __builtin_amdgcn_mfma_f32_32x32x16_bf16(pa1, PK(l1, h1), o0, 0, 0, 0);
;     o0 = __builtin_amdgcn_mfma_f32_32x32x16_bf16(pa2, PK(l2, h2), o0, 0, 0, 0);
;     o0 = __builtin_amdgcn_mfma_f32_32x32x16_bf16(pa3, PK(l3, h3), o0, 0, 0, 0);
;     asm volatile("s_waitcnt lgkmcnt(0)" ::: "memory"); __builtin_amdgcn_sched_barrier(0);
;     o1 = __builtin_amdgcn_mfma_f32_32x32x16_bf16(pa0, PK(m0, n0), o1, 0, 0, 0);
;     o1 = __builtin_amdgcn_mfma_f32_32x32x16_bf16(pa1, PK(m1, n1), o1, 0, 0, 0);
;     o1 = __builtin_amdgcn_mfma_f32_32x32x16_bf16(pa2, PK(m2, n2), o1, 0, 0, 0);
;     o1 = __builtin_amdgcn_mfma_f32_32x32x16_bf16(pa3, PK(m3, n3), o1, 0, 0, 0);
;     ...
; }
.LBB0_985:
	s_waitcnt lgkmcnt(3)
	v_mfma_f32_32x32x16_bf16 v[64:79], v[168:171], v[96:99], v[32:47]
	s_waitcnt lgkmcnt(2)
	v_mfma_f32_32x32x16_bf16 v[48:63], v[162:165], v[96:99], v[32:47]
	s_waitcnt lgkmcnt(1)
	v_mfma_f32_32x32x16_bf16 v[64:79], v[146:149], v[100:103], v[64:79]
	ds_read_b128 v[168:171], v157 offset:13376
	ds_read_b128 v[162:165], v157 offset:20032
	s_waitcnt lgkmcnt(2)
	v_mfma_f32_32x32x16_bf16 v[48:63], v[150:153], v[100:103], v[48:63]
	s_waitcnt lgkmcnt(1)
	v_mfma_f32_32x32x16_bf16 v[64:79], v[168:171], v[104:107], v[64:79]
	ds_read_b128 v[146:149], v157 offset:13408
	ds_read_b128 v[150:153], v157 offset:20064
	s_waitcnt lgkmcnt(2)
	v_mfma_f32_32x32x16_bf16 v[48:63], v[162:165], v[104:107], v[48:63]
	s_waitcnt lgkmcnt(1)
	v_mfma_f32_32x32x16_bf16 v[64:79], v[146:149], v[108:111], v[64:79]
	ds_read_b128 v[168:171], v157 offset:13440
	ds_read_b128 v[162:165], v157 offset:20096
	s_waitcnt lgkmcnt(2)
	v_mfma_f32_32x32x16_bf16 v[48:63], v[150:153], v[108:111], v[48:63]
	s_waitcnt lgkmcnt(1)
	v_mfma_f32_32x32x16_bf16 v[64:79], v[168:171], v[112:115], v[64:79]
	ds_read_b128 v[150:153], v157 offset:13472
	ds_read_b128 v[172:175], v157 offset:20128
	ds_read_b64_tr_b16 v[168:169], v199 offset:0
	ds_read_b64_tr_b16 v[170:171], v199 offset:0x100
	s_waitcnt lgkmcnt(4)
	v_mfma_f32_32x32x16_bf16 v[48:63], v[162:165], v[112:115], v[48:63]
	ds_read_b64_tr_b16 v[146:147], v199 offset:0x800
	ds_read_b64_tr_b16 v[148:149], v199 offset:0x900
	ds_read_b64_tr_b16 v[182:183], v199 offset:0x1000
	ds_read_b64_tr_b16 v[184:185], v199 offset:0x1100
	ds_read_b64_tr_b16 v[186:187], v199 offset:0x1800
	ds_read_b64_tr_b16 v[188:189], v199 offset:0x1900
	ds_read_b64_tr_b16 v[190:191], v199 offset:0x200
	ds_read_b64_tr_b16 v[192:193], v199 offset:0x300
	s_waitcnt lgkmcnt(11)
	v_mfma_f32_32x32x16_bf16 v[64:79], v[150:153], v[116:119], v[64:79]
	ds_read_b64_tr_b16 v[150:151], v199 offset:0xa00
	ds_read_b64_tr_b16 v[152:153], v199 offset:0xb00
	ds_read_b64_tr_b16 v[208:209], v199 offset:0x1200
	ds_read_b64_tr_b16 v[210:211], v199 offset:0x1300
	ds_read_b64_tr_b16 v[212:213], v199 offset:0x1a00
	ds_read_b64_tr_b16 v[214:215], v199 offset:0x1b00
	s_waitcnt lgkmcnt(0)
	v_mfma_f32_32x32x16_bf16 v[48:63], v[172:175], v[116:119], v[48:63]
	v_mfma_f32_32x32x16_bf16 v[0:15], v[92:95], v[168:171], v[0:15]
	v_mfma_f32_32x32x16_bf16 v[0:15], v[88:91], v[146:149], v[0:15]
	v_mfma_f32_32x32x16_bf16 v[0:15], v[84:87], v[182:185], v[0:15]
	v_mfma_f32_32x32x16_bf16 v[0:15], v[80:83], v[186:189], v[0:15]
	v_mfma_f32_32x32x16_bf16 v[16:31], v[92:95], v[190:193], v[16:31]
	s_waitcnt lgkmcnt(0)
	s_cmp_lg_u32 s40, 0
	s_cbranch_scc0 .Lmla_nobar6
	s_barrier
.Lmla_nobar6:
	v_mfma_f32_32x32x16_bf16 v[16:31], v[88:91], v[150:153], v[16:31]
	v_mfma_f32_32x32x16_bf16 v[16:31], v[84:87], v[208:211], v[16:31]
	s_cmp_lt_i32 s47, s54
	s_cbranch_scc0 .Lmla_w2_tail
	s_waitcnt vmcnt(3)
	ds_write_b128 v200, v[136:139]
	s_cmp_lg_u32 s8, 0
	s_cbranch_scc0 .Lmla_nope_o
	ds_write_b128 v239, v[140:143] offset:128

; __device__ __forceinline__ void mla_softmax_rel_kp(f32x16& p0, f32x16& p1, f32x16& negm, bool first, float& l_reg, float& alpha, bf16x8& pa0, bf16x8& pa1, bf16x8& pa2, bf16x8& pa3) {
;     ...
;         for (int r = 0; r < 16; ++r) { negm[r] = nm; p0[r] -= d; p1[r] -= d; }
;     }
; #pragma unroll
;     for (int r = 0; r < 16; ++r) { p0[r] = __builtin_amdgcn_exp2f(p0[r]); p1[r] = __builtin_amdgcn_exp2f(p1[r]); }
;     float ps = 0.f;
; #pragma unroll
;     for (int r = 0; r < 16; ++r) ps += p0[r];
; #pragma unroll
;     for (int r = 0; r < 16; ++r) ps += p1[r];
;     { auto rr = __builtin_amdgcn_permlane32_swap(__float_as_uint(ps), __float_as_uint(ps), false, false); ps = __uint_as_float(rr[0]) + __uint_as_float(rr[1]); }
;     l_reg = l_reg * alpha + ps;
.LBB0_991:
	v_mfma_f32_32x32x16_bf16 v[16:31], v[80:83], v[212:215], v[16:31]
	v_exp_f32_e32 v218, v64
	v_exp_f32_e32 v219, v65
	v_exp_f32_e32 v220, v66
	v_exp_f32_e32 v221, v67
	v_add_f32_e32 v173, v218, v220
	v_exp_f32_e32 v222, v68
	v_add_f32_e32 v174, v219, v221
	v_exp_f32_e32 v223, v69
	v_add_f32_e32 v173, v222, v173
	v_exp_f32_e32 v224, v70
	v_add_f32_e32 v174, v223, v174
	v_exp_f32_e32 v225, v71
	v_add_f32_e32 v173, v224, v173
	v_exp_f32_e32 v226, v72
	v_add_f32_e32 v174, v225, v174
	v_exp_f32_e32 v227, v73
	v_add_f32_e32 v173, v226, v173
	v_exp_f32_e32 v228, v74
	v_add_f32_e32 v174, v227, v174
	v_exp_f32_e32 v229, v75
	v_add_f32_e32 v173, v228, v173
	v_exp_f32_e32 v230, v76
	v_add_f32_e32 v174, v229, v174
	v_exp_f32_e32 v231, v77
	v_add_f32_e32 v173, v230, v173
	v_exp_f32_e32 v232, v78
	v_add_f32_e32 v174, v231, v174
	v_exp_f32_e32 v233, v79
	v_add_f32_e32 v173, v232, v173
	v_exp_f32_e32 v234, v48
	v_add_f32_e32 v174, v233, v174
	v_exp_f32_e32 v240, v49
	v_add_f32_e32 v173, v234, v173
	v_exp_f32_e32 v241, v50
	v_add_f32_e32 v174, v240, v174
	v_exp_f32_e32 v242, v51
	v_add_f32_e32 v173, v241, v173
	v_exp_f32_e32 v243, v52
	v_add_f32_e32 v174, v242, v174
	v_exp_f32_e32 v244, v53
	v_add_f32_e32 v173, v243, v173
	v_exp_f32_e32 v245, v54
	v_add_f32_e32 v174, v244, v174
	v_exp_f32_e32 v246, v55
	v_add_f32_e32 v173, v245, v173
	v_exp_f32_e32 v247, v56
	v_add_f32_e32 v174, v246, v174
	v_exp_f32_e32 v248, v57
	v_add_f32_e32 v173, v247, v173
	v_exp_f32_e32 v249, v58
	v_add_f32_e32 v174, v248, v174
	v_exp_f32_e32 v250, v59
	v_add_f32_e32 v173, v249, v173
	v_exp_f32_e32 v251, v60
	v_add_f32_e32 v174, v250, v174
	v_exp_f32_e32 v252, v61
	v_add_f32_e32 v173, v251, v173
	v_exp_f32_e32 v253, v62
	v_add_f32_e32 v174, v252, v174
	v_exp_f32_e32 v172, v63
	v_add_f32_e32 v173, v253, v173
	v_add_f32_e32 v174, v172, v174
	v_add_f32_e32 v173, v173, v174
	v_cmp_ge_f32_e32 vcc, 0x47800000, v173
	s_cmp_eq_u64 vcc, exec
	s_cbranch_scc0 .LBB0_996
	v_add_f32_e32 v236, v236, v173
